# gate-column pass after G1: 10 serialized vmcnt(0) round trips replaced by two load batches (same accumulation order)
# speedup vs baseline: 1.0301x; 1.0301x over previous
; __device__ void panel_gates(const bf16_t* XB, const bf16_t* Wg  , float* gates, int r0) {
;     ...
;     const bf16_t* xa = XB + (size_t)(r0 + (2 * wid) * 16 + li) * 1024 + kq * 8;
;     const bf16_t* xb = xa + 16 * 1024;
;     const bf16_t* wp = Wg + (size_t)li * 1024 + kq * 8;
;     f32x4 acc0 = {0.f, 0.f, 0.f, 0.f}, acc1 = {0.f, 0.f, 0.f, 0.f};
;     for (int kc = 0; kc < 4; ++kc) {
;         bf16x8 wf[8], x0[8], x1[8];
; #pragma unroll
;         for (int u = 0; u < 8; ++u) { const int ko = (kc * 8 + u) * 32; wf[u] = *(const bf16x8*)(wp + ko); x0[u] = *(const bf16x8*)(xa + ko); x1[u] = *(const bf16x8*)(xb + ko); }
; #pragma unroll
;         for (int u = 0; u < 8; ++u) { acc0 = __builtin_amdgcn_mfma_f32_16x16x32_bf16(wf[u], x0[u], acc0, 0, 0, 0); acc1 = __builtin_amdgcn_mfma_f32_16x16x32_bf16(wf[u], x1[u], acc1, 0, 0, 0); }
.LBB0_78:
	v_mov_b32_e32 v6, v176
	s_barrier
	s_mov_b64 s[4:5], 0x18600000
	v_and_b32_e32 v7, 15, v6
	v_ashrrev_i32_e32 v0, 1, v6
	v_and_b32_e32 v0, 0xffffffe0, v0
	v_or_b32_e32 v1, s27, v7
	v_add_u32_e32 v2, v1, v0
	v_ashrrev_i32_e32 v3, 31, v2
	v_lshlrev_b64 v[0:1], 11, v[2:3]
	v_lshl_add_u64 v[4:5], s[76:77], 0, v[0:1]
	v_mov_b32_e32 v1, 0
	v_and_b32_e32 v0, 48, v6
	v_lshlrev_b32_e32 v6, 11, v7
	v_mov_b32_e32 v7, v1
	v_lshl_add_u64 v[6:7], s[78:79], 0, v[6:7]
	v_lshl_add_u64 v[8:9], v[6:7], 0, v[0:1]
	s_mov_b32 s3, 0x18600000
	v_lshl_add_u64 v[6:7], v[8:9], 0, s[4:5]
	v_add_co_u32_e32 v8, vcc, s3, v8
	v_lshl_add_u64 v[4:5], v[4:5], 0, v[0:1]
	s_nop 0
	v_addc_co_u32_e32 v9, vcc, 0, v9, vcc
	s_mov_b32 s3, 0x8000
	v_add_co_u32_e32 v8, vcc, s3, v4
	s_add_u32 s4, s78, 0x18fe0000
	s_nop 0
	v_addc_co_u32_e32 v9, vcc, 0, v5, vcc
	s_addc_u32 s5, s79, 0
	global_load_dwordx4 v[20:23], v[6:7], off
	global_load_dwordx4 v[84:87], v[4:5], off
	global_load_dwordx4 v[180:183], v[8:9], off
	global_load_dwordx4 v[24:27], v[6:7], off offset:64
	global_load_dwordx4 v[88:91], v[4:5], off offset:64
	global_load_dwordx4 v[184:187], v[8:9], off offset:64
	global_load_dwordx4 v[28:31], v[6:7], off offset:128
	global_load_dwordx4 v[92:95], v[4:5], off offset:128
	global_load_dwordx4 v[188:191], v[8:9], off offset:128
	global_load_dwordx4 v[32:35], v[6:7], off offset:192
	global_load_dwordx4 v[96:99], v[4:5], off offset:192
	global_load_dwordx4 v[192:195], v[8:9], off offset:192
	global_load_dwordx4 v[36:39], v[6:7], off offset:256
	global_load_dwordx4 v[100:103], v[4:5], off offset:256
	global_load_dwordx4 v[196:199], v[8:9], off offset:256
	global_load_dwordx4 v[40:43], v[6:7], off offset:320
	global_load_dwordx4 v[104:107], v[4:5], off offset:320
	global_load_dwordx4 v[200:203], v[8:9], off offset:320
	global_load_dwordx4 v[44:47], v[6:7], off offset:384
	global_load_dwordx4 v[108:111], v[4:5], off offset:384
	global_load_dwordx4 v[204:207], v[8:9], off offset:384
	global_load_dwordx4 v[48:51], v[6:7], off offset:448
	global_load_dwordx4 v[112:115], v[4:5], off offset:448
	global_load_dwordx4 v[208:211], v[8:9], off offset:448
	global_load_dwordx4 v[52:55], v[6:7], off offset:512
	global_load_dwordx4 v[116:119], v[4:5], off offset:512
	global_load_dwordx4 v[212:215], v[8:9], off offset:512
	global_load_dwordx4 v[56:59], v[6:7], off offset:576
	global_load_dwordx4 v[120:123], v[4:5], off offset:576
	global_load_dwordx4 v[216:219], v[8:9], off offset:576
	global_load_dwordx4 v[60:63], v[6:7], off offset:640
	global_load_dwordx4 v[124:127], v[4:5], off offset:640
	global_load_dwordx4 v[220:223], v[8:9], off offset:640
	global_load_dwordx4 v[64:67], v[6:7], off offset:704
	global_load_dwordx4 v[128:131], v[4:5], off offset:704
	global_load_dwordx4 v[224:227], v[8:9], off offset:704
	global_load_dwordx4 v[68:71], v[6:7], off offset:768
	global_load_dwordx4 v[132:135], v[4:5], off offset:768
	global_load_dwordx4 v[228:231], v[8:9], off offset:768
	global_load_dwordx4 v[72:75], v[6:7], off offset:832
	global_load_dwordx4 v[136:139], v[4:5], off offset:832
	global_load_dwordx4 v[232:235], v[8:9], off offset:832
	global_load_dwordx4 v[76:79], v[6:7], off offset:896
	global_load_dwordx4 v[140:143], v[4:5], off offset:896
	global_load_dwordx4 v[236:239], v[8:9], off offset:896
	global_load_dwordx4 v[80:83], v[6:7], off offset:960
	global_load_dwordx4 v[144:147], v[4:5], off offset:960
	global_load_dwordx4 v[240:243], v[8:9], off offset:960
	s_waitcnt vmcnt(0)
	v_mfma_f32_16x16x32_bf16 v[12:15], v[20:23], v[84:87], 0
	v_mfma_f32_16x16x32_bf16 v[16:19], v[20:23], v[180:183], 0
	global_load_dwordx4 v[20:23], v[6:7], off offset:1024
	global_load_dwordx4 v[84:87], v[4:5], off offset:1024
	global_load_dwordx4 v[180:183], v[8:9], off offset:1024
	v_mfma_f32_16x16x32_bf16 v[12:15], v[24:27], v[88:91], v[12:15]
	v_mfma_f32_16x16x32_bf16 v[16:19], v[24:27], v[184:187], v[16:19]
	global_load_dwordx4 v[24:27], v[6:7], off offset:1088
	global_load_dwordx4 v[88:91], v[4:5], off offset:1088
	global_load_dwordx4 v[184:187], v[8:9], off offset:1088
	v_mfma_f32_16x16x32_bf16 v[12:15], v[28:31], v[92:95], v[12:15]
	v_mfma_f32_16x16x32_bf16 v[16:19], v[28:31], v[188:191], v[16:19]
	global_load_dwordx4 v[28:31], v[6:7], off offset:1152
	global_load_dwordx4 v[92:95], v[4:5], off offset:1152
	global_load_dwordx4 v[188:191], v[8:9], off offset:1152
	v_mfma_f32_16x16x32_bf16 v[12:15], v[32:35], v[96:99], v[12:15]
	v_mfma_f32_16x16x32_bf16 v[16:19], v[32:35], v[192:195], v[16:19]
	global_load_dwordx4 v[32:35], v[6:7], off offset:1216
	global_load_dwordx4 v[96:99], v[4:5], off offset:1216
	global_load_dwordx4 v[192:195], v[8:9], off offset:1216
	v_mfma_f32_16x16x32_bf16 v[12:15], v[36:39], v[100:103], v[12:15]
	v_mfma_f32_16x16x32_bf16 v[16:19], v[36:39], v[196:199], v[16:19]
	global_load_dwordx4 v[36:39], v[6:7], off offset:1280
	global_load_dwordx4 v[100:103], v[4:5], off offset:1280
	global_load_dwordx4 v[196:199], v[8:9], off offset:1280
	v_mfma_f32_16x16x32_bf16 v[12:15], v[40:43], v[104:107], v[12:15]
	v_mfma_f32_16x16x32_bf16 v[16:19], v[40:43], v[200:203], v[16:19]
	global_load_dwordx4 v[40:43], v[6:7], off offset:1344
	global_load_dwordx4 v[104:107], v[4:5], off offset:1344
	global_load_dwordx4 v[200:203], v[8:9], off offset:1344
	v_mfma_f32_16x16x32_bf16 v[12:15], v[44:47], v[108:111], v[12:15]
	v_mfma_f32_16x16x32_bf16 v[16:19], v[44:47], v[204:207], v[16:19]
; __device__ void panel_gates(const bf16_t* XB, const bf16_t* Wg  , float* gates, int r0) {
;     ...
;     for (int kc = 0; kc < 4; ++kc) {
;         bf16x8 wf[8], x0[8], x1[8];
; #pragma unroll
;         for (int u = 0; u < 8; ++u) { const int ko = (kc * 8 + u) * 32; wf[u] = *(const bf16x8*)(wp + ko); x0[u] = *(const bf16x8*)(xa + ko); x1[u] = *(const bf16x8*)(xb + ko); }
; #pragma unroll
;         for (int u = 0; u < 8; ++u) { acc0 = __builtin_amdgcn_mfma_f32_16x16x32_bf16(wf[u], x0[u], acc0, 0, 0, 0); acc1 = __builtin_amdgcn_mfma_f32_16x16x32_bf16(wf[u], x1[u], acc1, 0, 0, 0); }
;     }
;     *(f32x4*)(gates + (size_t)(r0 + (2 * wid) * 16 + li) * 16 + kq * 4) = acc0;
;     *(f32x4*)(gates + (size_t)(r0 + (2 * wid + 1) * 16 + li) * 16 + kq * 4) = acc1;
	global_load_dwordx4 v[44:47], v[6:7], off offset:1408
	global_load_dwordx4 v[108:111], v[4:5], off offset:1408
	global_load_dwordx4 v[204:207], v[8:9], off offset:1408
	v_mfma_f32_16x16x32_bf16 v[12:15], v[48:51], v[112:115], v[12:15]
	v_mfma_f32_16x16x32_bf16 v[16:19], v[48:51], v[208:211], v[16:19]
	global_load_dwordx4 v[48:51], v[6:7], off offset:1472
	global_load_dwordx4 v[112:115], v[4:5], off offset:1472
	global_load_dwordx4 v[208:211], v[8:9], off offset:1472
	v_mfma_f32_16x16x32_bf16 v[12:15], v[52:55], v[116:119], v[12:15]
	v_mfma_f32_16x16x32_bf16 v[16:19], v[52:55], v[212:215], v[16:19]
	global_load_dwordx4 v[52:55], v[6:7], off offset:1536
	global_load_dwordx4 v[116:119], v[4:5], off offset:1536
	global_load_dwordx4 v[212:215], v[8:9], off offset:1536
	v_mfma_f32_16x16x32_bf16 v[12:15], v[56:59], v[120:123], v[12:15]
	v_mfma_f32_16x16x32_bf16 v[16:19], v[56:59], v[216:219], v[16:19]
	global_load_dwordx4 v[56:59], v[6:7], off offset:1600
	global_load_dwordx4 v[120:123], v[4:5], off offset:1600
	global_load_dwordx4 v[216:219], v[8:9], off offset:1600
	v_mfma_f32_16x16x32_bf16 v[12:15], v[60:63], v[124:127], v[12:15]
	v_mfma_f32_16x16x32_bf16 v[16:19], v[60:63], v[220:223], v[16:19]
	global_load_dwordx4 v[60:63], v[6:7], off offset:1664
	global_load_dwordx4 v[124:127], v[4:5], off offset:1664
	global_load_dwordx4 v[220:223], v[8:9], off offset:1664
	v_mfma_f32_16x16x32_bf16 v[12:15], v[64:67], v[128:131], v[12:15]
	v_mfma_f32_16x16x32_bf16 v[16:19], v[64:67], v[224:227], v[16:19]
	global_load_dwordx4 v[64:67], v[6:7], off offset:1728
	global_load_dwordx4 v[128:131], v[4:5], off offset:1728
	global_load_dwordx4 v[224:227], v[8:9], off offset:1728
	v_mfma_f32_16x16x32_bf16 v[12:15], v[68:71], v[132:135], v[12:15]
	v_mfma_f32_16x16x32_bf16 v[16:19], v[68:71], v[228:231], v[16:19]
	global_load_dwordx4 v[68:71], v[6:7], off offset:1792
	global_load_dwordx4 v[132:135], v[4:5], off offset:1792
	global_load_dwordx4 v[228:231], v[8:9], off offset:1792
	v_mfma_f32_16x16x32_bf16 v[12:15], v[72:75], v[136:139], v[12:15]
	v_mfma_f32_16x16x32_bf16 v[16:19], v[72:75], v[232:235], v[16:19]
	global_load_dwordx4 v[72:75], v[6:7], off offset:1856
	global_load_dwordx4 v[136:139], v[4:5], off offset:1856
	global_load_dwordx4 v[232:235], v[8:9], off offset:1856
	v_mfma_f32_16x16x32_bf16 v[12:15], v[76:79], v[140:143], v[12:15]
	v_mfma_f32_16x16x32_bf16 v[16:19], v[76:79], v[236:239], v[16:19]
	global_load_dwordx4 v[76:79], v[6:7], off offset:1920
	global_load_dwordx4 v[140:143], v[4:5], off offset:1920
	global_load_dwordx4 v[236:239], v[8:9], off offset:1920
	v_mfma_f32_16x16x32_bf16 v[12:15], v[80:83], v[144:147], v[12:15]
	v_mfma_f32_16x16x32_bf16 v[16:19], v[80:83], v[240:243], v[16:19]
	global_load_dwordx4 v[80:83], v[6:7], off offset:1984
	global_load_dwordx4 v[144:147], v[4:5], off offset:1984
	global_load_dwordx4 v[240:243], v[8:9], off offset:1984
	s_waitcnt vmcnt(0)
	v_mfma_f32_16x16x32_bf16 v[12:15], v[20:23], v[84:87], v[12:15]
	v_mfma_f32_16x16x32_bf16 v[16:19], v[20:23], v[180:183], v[16:19]
	v_mfma_f32_16x16x32_bf16 v[12:15], v[24:27], v[88:91], v[12:15]
	v_mfma_f32_16x16x32_bf16 v[16:19], v[24:27], v[184:187], v[16:19]
	v_mfma_f32_16x16x32_bf16 v[12:15], v[28:31], v[92:95], v[12:15]
	v_mfma_f32_16x16x32_bf16 v[16:19], v[28:31], v[188:191], v[16:19]
	v_mfma_f32_16x16x32_bf16 v[12:15], v[32:35], v[96:99], v[12:15]
	v_mfma_f32_16x16x32_bf16 v[16:19], v[32:35], v[192:195], v[16:19]
	v_mfma_f32_16x16x32_bf16 v[12:15], v[36:39], v[100:103], v[12:15]
	v_mfma_f32_16x16x32_bf16 v[16:19], v[36:39], v[196:199], v[16:19]
	v_mfma_f32_16x16x32_bf16 v[12:15], v[40:43], v[104:107], v[12:15]
	v_mfma_f32_16x16x32_bf16 v[16:19], v[40:43], v[200:203], v[16:19]
	v_mfma_f32_16x16x32_bf16 v[12:15], v[44:47], v[108:111], v[12:15]
	v_mfma_f32_16x16x32_bf16 v[16:19], v[44:47], v[204:207], v[16:19]
	v_mfma_f32_16x16x32_bf16 v[12:15], v[48:51], v[112:115], v[12:15]
	v_mfma_f32_16x16x32_bf16 v[16:19], v[48:51], v[208:211], v[16:19]
	v_mfma_f32_16x16x32_bf16 v[12:15], v[52:55], v[116:119], v[12:15]
	v_mfma_f32_16x16x32_bf16 v[16:19], v[52:55], v[212:215], v[16:19]
	v_mfma_f32_16x16x32_bf16 v[12:15], v[56:59], v[120:123], v[12:15]
	v_mfma_f32_16x16x32_bf16 v[16:19], v[56:59], v[216:219], v[16:19]
	v_mfma_f32_16x16x32_bf16 v[12:15], v[60:63], v[124:127], v[12:15]
	v_mfma_f32_16x16x32_bf16 v[16:19], v[60:63], v[220:223], v[16:19]
	v_mfma_f32_16x16x32_bf16 v[12:15], v[64:67], v[128:131], v[12:15]
	v_mfma_f32_16x16x32_bf16 v[16:19], v[64:67], v[224:227], v[16:19]
	v_mfma_f32_16x16x32_bf16 v[12:15], v[68:71], v[132:135], v[12:15]
	v_mfma_f32_16x16x32_bf16 v[16:19], v[68:71], v[228:231], v[16:19]
	v_mfma_f32_16x16x32_bf16 v[12:15], v[72:75], v[136:139], v[12:15]
	v_mfma_f32_16x16x32_bf16 v[16:19], v[72:75], v[232:235], v[16:19]
	v_mfma_f32_16x16x32_bf16 v[12:15], v[76:79], v[140:143], v[12:15]
	v_mfma_f32_16x16x32_bf16 v[16:19], v[76:79], v[236:239], v[16:19]
	v_mfma_f32_16x16x32_bf16 v[12:15], v[80:83], v[144:147], v[12:15]
	v_mfma_f32_16x16x32_bf16 v[16:19], v[80:83], v[240:243], v[16:19]
	v_lshlrev_b64 v[8:9], 6, v[2:3]
	v_lshl_add_u64 v[8:9], s[4:5], 0, v[8:9]
	v_lshl_add_u64 v[8:9], v[8:9], 0, v[0:1]
	v_add_u32_e32 v6, 16, v2
	v_ashrrev_i32_e32 v7, 31, v6
	v_lshlrev_b64 v[6:7], 6, v[6:7]
	v_lshl_add_u64 v[6:7], s[4:5], 0, v[6:7]
	v_lshl_add_u64 v[6:7], v[6:7], 0, v[0:1]
	s_nop 7
	global_store_dwordx4 v[8:9], v[12:15], off
	global_store_dwordx4 v[6:7], v[16:19], off
